# FFN-in K-loop phase rebalancing: next B fragment LDS reads moved from the 12-read phase into the DMA-only phase, with an earlier counted vmcnt publish
# speedup vs baseline: 1.0133x; 1.0133x over previous
; #define STAGE(P, BASE, LD, br, kt) do { const bf16* _gb = BASE + ((long)(br) * (LD) + (long)(kt) * BK); \
;     _Pragma("unroll") for (int _i = 0; _i < 2; ++_i) { \
;       __builtin_amdgcn_global_load_lds((const unsigned*)(_gb + ((&LD == &lda) ? offA[_i] : offB[_i])), \
;         (unsigned*)((char*)(P) + tidx_ * 16 + _i * 8192), 16, 0, 0); } } while (0)
; #define LDA(dst, b, h) _Pragma("unroll") for (int m = 0; m < 4; ++m) _Pragma("unroll") for (int k = 0; k < 2; ++k) \
;     dst[m][k] = *reinterpret_cast<const bf16x8*>(smem + (((b) * 2 + (h)) * 16384 + m * 2048 + k * 1024) + aoff)
; #define LDB(dst, b, h) _Pragma("unroll") for (int n = 0; n < 2; ++n) _Pragma("unroll") for (int k = 0; k < 2; ++k) \
;     dst[n][k] = *reinterpret_cast<const bf16x8*>(smem + (((b) * 2 + (h)) * 16384 + n * 2048 + k * 1024) + boff)
; #define WAIT_V(n) asm volatile("s_waitcnt vmcnt(" #n ")" ::: "memory")
; #define WAIT_L(n) asm volatile("s_waitcnt lgkmcnt(" #n ")" ::: "memory")
; #define BAR __builtin_amdgcn_s_barrier()
; #define SCHED __builtin_amdgcn_sched_barrier(0)
; template <class Epi, int NB>
; DEV void gemm_tile_nb(const bf16* __restrict__ A, int lda, long strideA, const bf16* __restrict__ Bt, int ldb, long strideB, int K, int brow, int bcol, Epi& epi) {
;     ...
;   f32x4 acc[2][2][4][2] = {};
;   bf16x8 At[4][2], B0[2][2], B1[2][2];
;   const int nt = K / BK;
;   const int lane_off_ = (fr * 64 + fq * 16) ^ ((fr >> 3) << 5);
;   const int aoff = wr * 8192 + lane_off_, boff = 65536 + wc * 4096 + lane_off_;
;   unsigned offA[2], offB[2];
; #pragma unroll
;   for (int _i = 0; _i < 2; ++_i) { int _r, _c; stage_rc(tidx_ * 16 + _i * 8192, _r, _c); offA[_i] = (unsigned)(_r * lda + _c); offB[_i] = (unsigned)(_r * ldb + _c); }
; #pragma unroll 1
;   for (int br = 0; br < NB; ++br) {
;   STAGE(SB(0, 0), Bt, ldb, bcol, 0); STAGE(SA(0, 0), A, lda, brow, 0);
;   STAGE(SB(0, 1), Bt, ldb, bcol + HALF, 0); STAGE(SA(0, 1), A, lda, brow + HALF, 0);
;   if (wr == 1) BAR;
;   WAIT_V(4); BAR;
;   STAGE(SB(1, 0), Bt, ldb, bcol, 1); STAGE(SA(1, 0), A, lda, brow, 1); STAGE(SB(1, 1), Bt, ldb, bcol + HALF, 1);
;   WAIT_V(6); BAR;
;   for (int t = 0; t < nt - 2; t += 2) {
;     LDB(B0, 0, 0); SCHED; LDA(At, 0, 0); STAGE(SA(1, 1), A, lda, brow + HALF, t + 1);
;     WAIT_L(8); BAR; WAIT_L(0); MMA(0, 0, At, B0); BAR; SCHED;
.Lffn_w6b:
	v_or_b32_e32 v24, 0x10000, v24
	v_lshl_add_u64 v[138:139], s[42:43], 0, v[2:3]
	v_mov_b32_e32 v2, 0
	v_lshl_add_u64 v[140:141], s[42:43], 0, v[4:5]
	s_mov_b32 s58, -2
	s_mov_b64 s[42:43], 0
	v_add_u32_e32 v145, 0, v24
	v_add_u32_e32 v0, 0, v23
	v_mov_b32_e32 v3, v2
	v_mov_b32_e32 v4, v2
	v_mov_b32_e32 v5, v2
	v_mov_b32_e32 v6, v2
	v_mov_b32_e32 v7, v2
	v_mov_b32_e32 v8, v2
	v_mov_b32_e32 v9, v2
	v_mov_b32_e32 v10, v2
	v_mov_b32_e32 v11, v2
	v_mov_b32_e32 v12, v2
	v_mov_b32_e32 v13, v2
	v_mov_b32_e32 v14, v2
	v_mov_b32_e32 v15, v2
	v_mov_b32_e32 v16, v2
	v_mov_b32_e32 v17, v2
	v_mov_b32_e32 v18, v2
	v_mov_b32_e32 v19, v2
	v_mov_b32_e32 v20, v2
	v_mov_b32_e32 v21, v2
	v_mov_b32_e32 v22, v2
	v_mov_b32_e32 v23, v2
	v_mov_b32_e32 v24, v2
	v_mov_b32_e32 v25, v2
	v_mov_b32_e32 v26, v2
	v_mov_b32_e32 v27, v2
	v_mov_b32_e32 v28, v2
	v_mov_b32_e32 v29, v2
	v_mov_b32_e32 v30, v2
	v_mov_b32_e32 v31, v2
	v_mov_b32_e32 v32, v2
	v_mov_b32_e32 v33, v2
	v_mov_b32_e32 v34, v2
	v_mov_b32_e32 v35, v2
	v_mov_b32_e32 v36, v2
	v_mov_b32_e32 v37, v2
	v_mov_b32_e32 v38, v2
	v_mov_b32_e32 v39, v2
	v_mov_b32_e32 v40, v2
	v_mov_b32_e32 v41, v2
	v_mov_b32_e32 v42, v2
	v_mov_b32_e32 v43, v2
	v_mov_b32_e32 v44, v2
	v_mov_b32_e32 v45, v2
	v_mov_b32_e32 v46, v2
	v_mov_b32_e32 v47, v2
	v_mov_b32_e32 v48, v2
	v_mov_b32_e32 v49, v2
	v_mov_b32_e32 v50, v2
	v_mov_b32_e32 v51, v2
	v_mov_b32_e32 v52, v2
	v_mov_b32_e32 v53, v2
	v_mov_b32_e32 v54, v2
	v_mov_b32_e32 v55, v2
	v_mov_b32_e32 v56, v2
	v_mov_b32_e32 v57, v2
	v_mov_b32_e32 v58, v2
	v_mov_b32_e32 v59, v2
	v_mov_b32_e32 v60, v2
	v_mov_b32_e32 v61, v2
	v_mov_b32_e32 v62, v2
	v_mov_b32_e32 v63, v2
	v_mov_b32_e32 v64, v2
	v_mov_b32_e32 v65, v2
	v_mov_b32_e32 v70, v2
	v_mov_b32_e32 v71, v2
	v_mov_b32_e32 v72, v2
	v_mov_b32_e32 v73, v2
	v_mov_b32_e32 v86, v2
	v_mov_b32_e32 v87, v2
	v_mov_b32_e32 v88, v2
	v_mov_b32_e32 v89, v2
	v_mov_b32_e32 v90, v2
	v_mov_b32_e32 v91, v2
	v_mov_b32_e32 v92, v2
	v_mov_b32_e32 v93, v2
	v_mov_b32_e32 v94, v2
	v_mov_b32_e32 v95, v2
	v_mov_b32_e32 v96, v2
	v_mov_b32_e32 v97, v2
	v_mov_b32_e32 v98, v2
	v_mov_b32_e32 v99, v2
	v_mov_b32_e32 v100, v2
	v_mov_b32_e32 v101, v2
	v_mov_b32_e32 v102, v2
	v_mov_b32_e32 v103, v2
	v_mov_b32_e32 v104, v2
	v_mov_b32_e32 v105, v2
	v_mov_b32_e32 v106, v2
	v_mov_b32_e32 v107, v2
	v_mov_b32_e32 v108, v2
	v_mov_b32_e32 v109, v2
	v_mov_b32_e32 v110, v2
	v_mov_b32_e32 v111, v2
	v_mov_b32_e32 v112, v2
	v_mov_b32_e32 v113, v2
	v_mov_b32_e32 v114, v2
	v_mov_b32_e32 v115, v2
	v_mov_b32_e32 v116, v2
	v_mov_b32_e32 v117, v2
	v_mov_b32_e32 v118, v2
	v_mov_b32_e32 v119, v2
	v_mov_b32_e32 v120, v2
	v_mov_b32_e32 v121, v2
	v_mov_b32_e32 v122, v2
	v_mov_b32_e32 v123, v2
	v_mov_b32_e32 v124, v2
	v_mov_b32_e32 v125, v2
	v_mov_b32_e32 v126, v2
	v_mov_b32_e32 v127, v2
	v_mov_b32_e32 v128, v2
	v_mov_b32_e32 v129, v2
	v_mov_b32_e32 v66, v2
	v_mov_b32_e32 v67, v2
	v_mov_b32_e32 v68, v2
	v_mov_b32_e32 v69, v2
	v_mov_b32_e32 v74, v2
	v_mov_b32_e32 v75, v2
	v_mov_b32_e32 v76, v2
	v_mov_b32_e32 v77, v2
	v_mov_b32_e32 v78, v2
	v_mov_b32_e32 v79, v2
	v_mov_b32_e32 v80, v2
	v_mov_b32_e32 v81, v2
	v_mov_b32_e32 v82, v2
	v_mov_b32_e32 v83, v2
	v_mov_b32_e32 v84, v2
	v_mov_b32_e32 v85, v2
	s_barrier
	ds_read_b128 v[162:165], v145
	ds_read_b128 v[166:169], v145 offset:1024
	ds_read_b128 v[170:173], v145 offset:2048
	ds_read_b128 v[174:177], v145 offset:3072
.LBB0_960:
	v_add_u32_e32 v159, 0xc000, v146
	v_lshl_add_u64 v[246:247], v[138:139], 0, s[42:43]
	v_readfirstlane_b32 s59, v159
	v_lshl_add_u64 v[160:161], v[246:247], 0, s[80:81]
	s_mov_b32 m0, s59
	ds_read_b128 v[184:187], v0
	ds_read_b128 v[188:191], v0 offset:1024
	ds_read_b128 v[192:195], v0 offset:2048
	ds_read_b128 v[196:199], v0 offset:3072
	ds_read_b128 v[200:203], v0 offset:4096
	ds_read_b128 v[218:221], v0 offset:5120
	ds_read_b128 v[222:225], v0 offset:6144
	ds_read_b128 v[226:229], v0 offset:7168
	global_load_lds_dwordx4 v[160:161], off
	v_add_u32_e32 v160, 0xe000, v146
	v_lshl_add_u64 v[248:249], v[140:141], 0, s[42:43]
	v_readfirstlane_b32 s59, v160
	v_lshl_add_u64 v[230:231], v[248:249], 0, s[80:81]
	s_mov_b32 m0, s59
	s_nop 0
	global_load_lds_dwordx4 v[230:231], off
	s_waitcnt lgkmcnt(8)
	s_barrier
	s_waitcnt lgkmcnt(0)
	s_setprio 1
	s_waitcnt lgkmcnt(0)
	v_mfma_f32_16x16x32_bf16 v[126:129], v[162:165], v[184:187], v[126:129]
	v_mfma_f32_16x16x32_bf16 v[122:125], v[170:173], v[184:187], v[122:125]
	v_mfma_f32_16x16x32_bf16 v[118:121], v[162:165], v[192:195], v[118:121]
	v_mfma_f32_16x16x32_bf16 v[114:117], v[170:173], v[192:195], v[114:117]
	v_mfma_f32_16x16x32_bf16 v[110:113], v[162:165], v[200:203], v[110:113]
	v_mfma_f32_16x16x32_bf16 v[106:109], v[170:173], v[200:203], v[106:109]
	v_mfma_f32_16x16x32_bf16 v[102:105], v[162:165], v[222:225], v[102:105]
	v_mfma_f32_16x16x32_bf16 v[98:101], v[170:173], v[222:225], v[98:101]
	v_mfma_f32_16x16x32_bf16 v[126:129], v[166:169], v[188:191], v[126:129]
	v_mfma_f32_16x16x32_bf16 v[122:125], v[174:177], v[188:191], v[122:125]
	v_mfma_f32_16x16x32_bf16 v[118:121], v[166:169], v[196:199], v[118:121]
	v_mfma_f32_16x16x32_bf16 v[114:117], v[174:177], v[196:199], v[114:117]
	v_mfma_f32_16x16x32_bf16 v[110:113], v[166:169], v[218:221], v[110:113]
	v_mfma_f32_16x16x32_bf16 v[106:109], v[174:177], v[218:221], v[106:109]
	v_mfma_f32_16x16x32_bf16 v[102:105], v[166:169], v[226:229], v[102:105]
	v_mfma_f32_16x16x32_bf16 v[98:101], v[174:177], v[226:229], v[98:101]
	s_setprio 0
	s_barrier
; #define STAGE(P, BASE, LD, br, kt) do { const bf16* _gb = BASE + ((long)(br) * (LD) + (long)(kt) * BK); \
;     _Pragma("unroll") for (int _i = 0; _i < 2; ++_i) { \
;       __builtin_amdgcn_global_load_lds((const unsigned*)(_gb + ((&LD == &lda) ? offA[_i] : offB[_i])), \
;         (unsigned*)((char*)(P) + tidx_ * 16 + _i * 8192), 16, 0, 0); } } while (0)
; #define LDA(dst, b, h) _Pragma("unroll") for (int m = 0; m < 4; ++m) _Pragma("unroll") for (int k = 0; k < 2; ++k) \
;     dst[m][k] = *reinterpret_cast<const bf16x8*>(smem + (((b) * 2 + (h)) * 16384 + m * 2048 + k * 1024) + aoff)
; #define LDB(dst, b, h) _Pragma("unroll") for (int n = 0; n < 2; ++n) _Pragma("unroll") for (int k = 0; k < 2; ++k) \
;     dst[n][k] = *reinterpret_cast<const bf16x8*>(smem + (((b) * 2 + (h)) * 16384 + n * 2048 + k * 1024) + boff)
; #define MMA(ai, bj, At_, Bt_) do { __builtin_amdgcn_s_setprio(1); \
;     _Pragma("unroll") for (int m = 0; m < 4; ++m) _Pragma("unroll") for (int n = 0; n < 2; ++n) _Pragma("unroll") for (int k = 0; k < 2; ++k) \
;       acc[ai][bj][m][n] = __builtin_amdgcn_mfma_f32_16x16x32_bf16(Bt_[n][k], At_[m][k], acc[ai][bj][m][n], 0, 0, 0); \
;     __builtin_amdgcn_s_setprio(0); } while (0)
; #define WAIT_V(n) asm volatile("s_waitcnt vmcnt(" #n ")" ::: "memory")
; #define WAIT_L(n) asm volatile("s_waitcnt lgkmcnt(" #n ")" ::: "memory")
; #define BAR __builtin_amdgcn_s_barrier()
; #define SCHED __builtin_amdgcn_sched_barrier(0)
; template <class Epi, int NB>
; DEV void gemm_tile_nb(const bf16* __restrict__ A, int lda, long strideA, const bf16* __restrict__ Bt, int ldb, long strideB, int K, int brow, int bcol, Epi& epi) {
;     ...
;     LDB(B0, 0, 0); SCHED; LDA(At, 0, 0); STAGE(SA(1, 1), A, lda, brow + HALF, t + 1);
;     WAIT_L(8); BAR; WAIT_L(0); MMA(0, 0, At, B0); BAR; SCHED;
;     LDB(B1, 0, 1); STAGE(SB(0, 0), Bt, ldb, bcol, t + 2);
;     BAR; WAIT_L(0); MMA(0, 1, At, B1); BAR;
;     LDA(At, 0, 1); STAGE(SA(0, 0), A, lda, brow, t + 2);
;     BAR; WAIT_L(0); MMA(1, 0, At, B0); BAR; SCHED;
;     STAGE(SB(0, 1), Bt, ldb, bcol + HALF, t + 2);
;     WAIT_V(6); BAR; MMA(1, 1, At, B1); BAR;
;     LDB(B0, 1, 0); SCHED; LDA(At, 1, 0); STAGE(SA(0, 1), A, lda, brow + HALF, t + 2);
;     WAIT_L(8); BAR; WAIT_L(0); MMA(0, 0, At, B0); BAR; SCHED;
	v_lshl_add_u64 v[204:205], v[134:135], 0, s[42:43]
	v_readfirstlane_b32 s59, v144
	v_lshl_add_u64 v[214:215], v[204:205], 0, s[72:73]
	s_mov_b32 m0, s59
	ds_read_b128 v[230:233], v145 offset:16384
	ds_read_b128 v[234:237], v145 offset:17408
	ds_read_b128 v[238:241], v145 offset:18432
	ds_read_b128 v[242:245], v145 offset:19456
	global_load_lds_dwordx4 v[214:215], off
	v_lshl_add_u64 v[214:215], v[136:137], 0, s[42:43]
	v_readfirstlane_b32 s59, v148
	v_lshl_add_u64 v[208:209], v[214:215], 0, s[72:73]
	s_mov_b32 m0, s59
	s_nop 0
	global_load_lds_dwordx4 v[208:209], off
	s_barrier
	s_waitcnt lgkmcnt(0)
	s_setprio 1
	s_waitcnt lgkmcnt(0)
	v_mfma_f32_16x16x32_bf16 v[94:97], v[230:233], v[184:187], v[94:97]
	v_mfma_f32_16x16x32_bf16 v[90:93], v[238:241], v[184:187], v[90:93]
	v_mfma_f32_16x16x32_bf16 v[86:89], v[230:233], v[192:195], v[86:89]
	v_mfma_f32_16x16x32_bf16 v[70:73], v[238:241], v[192:195], v[70:73]
	v_mfma_f32_16x16x32_bf16 v[62:65], v[230:233], v[200:203], v[62:65]
	v_mfma_f32_16x16x32_bf16 v[58:61], v[238:241], v[200:203], v[58:61]
	v_mfma_f32_16x16x32_bf16 v[54:57], v[230:233], v[222:225], v[54:57]
	v_mfma_f32_16x16x32_bf16 v[50:53], v[238:241], v[222:225], v[50:53]
	v_mfma_f32_16x16x32_bf16 v[94:97], v[234:237], v[188:191], v[94:97]
	v_mfma_f32_16x16x32_bf16 v[90:93], v[242:245], v[188:191], v[90:93]
	v_mfma_f32_16x16x32_bf16 v[86:89], v[234:237], v[196:199], v[86:89]
	v_mfma_f32_16x16x32_bf16 v[70:73], v[242:245], v[196:199], v[70:73]
	v_mfma_f32_16x16x32_bf16 v[62:65], v[234:237], v[218:221], v[62:65]
	v_mfma_f32_16x16x32_bf16 v[58:61], v[242:245], v[218:221], v[58:61]
	v_mfma_f32_16x16x32_bf16 v[54:57], v[234:237], v[226:229], v[54:57]
	v_mfma_f32_16x16x32_bf16 v[50:53], v[242:245], v[226:229], v[50:53]
	s_setprio 0
	v_readfirstlane_b32 s59, v146
	v_lshl_add_u64 v[208:209], v[246:247], 0, s[72:73]
	s_mov_b32 m0, s59
	v_readfirstlane_b32 s59, v150
	s_barrier
	ds_read_b128 v[184:187], v0 offset:16384
	ds_read_b128 v[188:191], v0 offset:17408
	ds_read_b128 v[192:195], v0 offset:18432
	ds_read_b128 v[196:199], v0 offset:19456
	ds_read_b128 v[200:203], v0 offset:20480
	ds_read_b128 v[218:221], v0 offset:21504
	ds_read_b128 v[222:225], v0 offset:22528
	ds_read_b128 v[226:229], v0 offset:23552
	global_load_lds_dwordx4 v[208:209], off
	v_lshl_add_u64 v[208:209], v[248:249], 0, s[72:73]
	s_mov_b32 m0, s59
	s_nop 0
	global_load_lds_dwordx4 v[208:209], off
	s_waitcnt vmcnt(10)
	s_barrier
	s_waitcnt lgkmcnt(0)
	s_setprio 1
	s_waitcnt lgkmcnt(0)
	v_mfma_f32_16x16x32_bf16 v[46:49], v[162:165], v[184:187], v[46:49]
	v_mfma_f32_16x16x32_bf16 v[42:45], v[170:173], v[184:187], v[42:45]
	v_mfma_f32_16x16x32_bf16 v[38:41], v[162:165], v[192:195], v[38:41]
	v_mfma_f32_16x16x32_bf16 v[34:37], v[170:173], v[192:195], v[34:37]
	v_mfma_f32_16x16x32_bf16 v[30:33], v[162:165], v[200:203], v[30:33]
	v_mfma_f32_16x16x32_bf16 v[26:29], v[170:173], v[200:203], v[26:29]
	v_mfma_f32_16x16x32_bf16 v[22:25], v[162:165], v[222:225], v[22:25]
	v_mfma_f32_16x16x32_bf16 v[18:21], v[170:173], v[222:225], v[18:21]
	v_mfma_f32_16x16x32_bf16 v[46:49], v[166:169], v[188:191], v[46:49]
	v_mfma_f32_16x16x32_bf16 v[42:45], v[174:177], v[188:191], v[42:45]
	v_mfma_f32_16x16x32_bf16 v[38:41], v[166:169], v[196:199], v[38:41]
	v_mfma_f32_16x16x32_bf16 v[34:37], v[174:177], v[196:199], v[34:37]
	v_mfma_f32_16x16x32_bf16 v[30:33], v[166:169], v[218:221], v[30:33]
	v_mfma_f32_16x16x32_bf16 v[26:29], v[174:177], v[218:221], v[26:29]
	v_mfma_f32_16x16x32_bf16 v[22:25], v[166:169], v[226:229], v[22:25]
	v_mfma_f32_16x16x32_bf16 v[18:21], v[174:177], v[226:229], v[18:21]
	s_setprio 0
	s_barrier
	v_readfirstlane_b32 s59, v147
	v_lshl_add_u64 v[208:209], v[204:205], 0, s[82:83]
	s_mov_b32 m0, s59
	v_readfirstlane_b32 s59, v151
	global_load_lds_dwordx4 v[208:209], off
	v_lshl_add_u64 v[208:209], v[214:215], 0, s[82:83]
	s_mov_b32 m0, s59
	s_nop 0
	global_load_lds_dwordx4 v[208:209], off
	ds_read_b128 v[162:165], v145 offset:32768
	ds_read_b128 v[166:169], v145 offset:33792
	ds_read_b128 v[170:173], v145 offset:34816
	ds_read_b128 v[174:177], v145 offset:35840
	s_waitcnt vmcnt(6)
	s_barrier
	s_setprio 1
	v_mfma_f32_16x16x32_bf16 v[14:17], v[230:233], v[184:187], v[14:17]
	v_mfma_f32_16x16x32_bf16 v[10:13], v[238:241], v[184:187], v[10:13]
	v_mfma_f32_16x16x32_bf16 v[6:9], v[230:233], v[192:195], v[6:9]
	v_mfma_f32_16x16x32_bf16 v[2:5], v[238:241], v[192:195], v[2:5]
	v_mfma_f32_16x16x32_bf16 v[66:69], v[230:233], v[200:203], v[66:69]
	v_mfma_f32_16x16x32_bf16 v[74:77], v[238:241], v[200:203], v[74:77]
	v_mfma_f32_16x16x32_bf16 v[78:81], v[230:233], v[222:225], v[78:81]
	v_mfma_f32_16x16x32_bf16 v[82:85], v[238:241], v[222:225], v[82:85]
	v_mfma_f32_16x16x32_bf16 v[14:17], v[234:237], v[188:191], v[14:17]
	v_mfma_f32_16x16x32_bf16 v[10:13], v[242:245], v[188:191], v[10:13]
	v_mfma_f32_16x16x32_bf16 v[6:9], v[234:237], v[196:199], v[6:9]
	v_mfma_f32_16x16x32_bf16 v[2:5], v[242:245], v[196:199], v[2:5]
	v_mfma_f32_16x16x32_bf16 v[66:69], v[234:237], v[218:221], v[66:69]
	v_mfma_f32_16x16x32_bf16 v[74:77], v[242:245], v[218:221], v[74:77]
	v_mfma_f32_16x16x32_bf16 v[78:81], v[234:237], v[226:229], v[78:81]
	v_mfma_f32_16x16x32_bf16 v[82:85], v[242:245], v[226:229], v[82:85]
	s_setprio 0
	s_barrier
	v_readfirstlane_b32 s59, v149
	v_lshl_add_u64 v[208:209], v[246:247], 0, s[82:83]
	s_mov_b32 m0, s59
	v_readfirstlane_b32 s59, v152
	ds_read_b128 v[184:187], v0 offset:32768
	ds_read_b128 v[188:191], v0 offset:33792
	ds_read_b128 v[192:195], v0 offset:34816
	ds_read_b128 v[196:199], v0 offset:35840
	ds_read_b128 v[200:203], v0 offset:36864
	ds_read_b128 v[218:221], v0 offset:37888
	ds_read_b128 v[222:225], v0 offset:38912
	ds_read_b128 v[226:229], v0 offset:39936
	global_load_lds_dwordx4 v[208:209], off
	v_lshl_add_u64 v[208:209], v[248:249], 0, s[82:83]
	s_mov_b32 m0, s59
	s_nop 0
	global_load_lds_dwordx4 v[208:209], off
	s_waitcnt lgkmcnt(8)
	s_barrier
; #define STAGE(P, BASE, LD, br, kt) do { const bf16* _gb = BASE + ((long)(br) * (LD) + (long)(kt) * BK); \
;     _Pragma("unroll") for (int _i = 0; _i < 2; ++_i) { \
;       __builtin_amdgcn_global_load_lds((const unsigned*)(_gb + ((&LD == &lda) ? offA[_i] : offB[_i])), \
;         (unsigned*)((char*)(P) + tidx_ * 16 + _i * 8192), 16, 0, 0); } } while (0)
; #define LDA(dst, b, h) _Pragma("unroll") for (int m = 0; m < 4; ++m) _Pragma("unroll") for (int k = 0; k < 2; ++k) \
;     dst[m][k] = *reinterpret_cast<const bf16x8*>(smem + (((b) * 2 + (h)) * 16384 + m * 2048 + k * 1024) + aoff)
; #define LDB(dst, b, h) _Pragma("unroll") for (int n = 0; n < 2; ++n) _Pragma("unroll") for (int k = 0; k < 2; ++k) \
;     dst[n][k] = *reinterpret_cast<const bf16x8*>(smem + (((b) * 2 + (h)) * 16384 + n * 2048 + k * 1024) + boff)
; #define MMA(ai, bj, At_, Bt_) do { __builtin_amdgcn_s_setprio(1); \
;     _Pragma("unroll") for (int m = 0; m < 4; ++m) _Pragma("unroll") for (int n = 0; n < 2; ++n) _Pragma("unroll") for (int k = 0; k < 2; ++k) \
;       acc[ai][bj][m][n] = __builtin_amdgcn_mfma_f32_16x16x32_bf16(Bt_[n][k], At_[m][k], acc[ai][bj][m][n], 0, 0, 0); \
;     __builtin_amdgcn_s_setprio(0); } while (0)
; #define WAIT_V(n) asm volatile("s_waitcnt vmcnt(" #n ")" ::: "memory")
; #define WAIT_L(n) asm volatile("s_waitcnt lgkmcnt(" #n ")" ::: "memory")
; #define BAR __builtin_amdgcn_s_barrier()
; #define SCHED __builtin_amdgcn_sched_barrier(0)
; template <class Epi, int NB>
; DEV void gemm_tile_nb(const bf16* __restrict__ A, int lda, long strideA, const bf16* __restrict__ Bt, int ldb, long strideB, int K, int brow, int bcol, Epi& epi) {
;     ...
;     LDB(B0, 1, 0); SCHED; LDA(At, 1, 0); STAGE(SA(0, 1), A, lda, brow + HALF, t + 2);
;     WAIT_L(8); BAR; WAIT_L(0); MMA(0, 0, At, B0); BAR; SCHED;
;     LDB(B1, 1, 1); STAGE(SB(1, 0), Bt, ldb, bcol, t + 3);
;     BAR; WAIT_L(0); MMA(0, 1, At, B1); BAR;
;     LDA(At, 1, 1); STAGE(SA(1, 0), A, lda, brow, t + 3);
;     BAR; WAIT_L(0); MMA(1, 0, At, B0); BAR; SCHED;
;     STAGE(SB(1, 1), Bt, ldb, bcol + HALF, t + 3);
;     WAIT_V(6); BAR; MMA(1, 1, At, B1); BAR;
	s_waitcnt lgkmcnt(0)
	s_setprio 1
	s_waitcnt lgkmcnt(0)
	v_mfma_f32_16x16x32_bf16 v[126:129], v[162:165], v[184:187], v[126:129]
	v_mfma_f32_16x16x32_bf16 v[122:125], v[170:173], v[184:187], v[122:125]
	v_mfma_f32_16x16x32_bf16 v[118:121], v[162:165], v[192:195], v[118:121]
	v_mfma_f32_16x16x32_bf16 v[114:117], v[170:173], v[192:195], v[114:117]
	v_mfma_f32_16x16x32_bf16 v[110:113], v[162:165], v[200:203], v[110:113]
	v_mfma_f32_16x16x32_bf16 v[106:109], v[170:173], v[200:203], v[106:109]
	v_mfma_f32_16x16x32_bf16 v[102:105], v[162:165], v[222:225], v[102:105]
	v_mfma_f32_16x16x32_bf16 v[98:101], v[170:173], v[222:225], v[98:101]
	v_mfma_f32_16x16x32_bf16 v[126:129], v[166:169], v[188:191], v[126:129]
	v_mfma_f32_16x16x32_bf16 v[122:125], v[174:177], v[188:191], v[122:125]
	v_mfma_f32_16x16x32_bf16 v[118:121], v[166:169], v[196:199], v[118:121]
	v_mfma_f32_16x16x32_bf16 v[114:117], v[174:177], v[196:199], v[114:117]
	v_mfma_f32_16x16x32_bf16 v[110:113], v[166:169], v[218:221], v[110:113]
	v_mfma_f32_16x16x32_bf16 v[106:109], v[174:177], v[218:221], v[106:109]
	v_mfma_f32_16x16x32_bf16 v[102:105], v[166:169], v[226:229], v[102:105]
	v_mfma_f32_16x16x32_bf16 v[98:101], v[174:177], v[226:229], v[98:101]
	s_setprio 0
	s_barrier
	v_readfirstlane_b32 s59, v153
	v_lshl_add_u64 v[208:209], v[204:205], 0, s[84:85]
	s_mov_b32 m0, s59
	v_readfirstlane_b32 s59, v154
	ds_read_b128 v[230:233], v145 offset:49152
	ds_read_b128 v[234:237], v145 offset:50176
	ds_read_b128 v[238:241], v145 offset:51200
	ds_read_b128 v[242:245], v145 offset:52224
	global_load_lds_dwordx4 v[208:209], off
	v_lshl_add_u64 v[208:209], v[214:215], 0, s[84:85]
	s_mov_b32 m0, s59
	s_nop 0
	global_load_lds_dwordx4 v[208:209], off
	s_barrier
	s_waitcnt lgkmcnt(0)
	s_setprio 1
	s_waitcnt lgkmcnt(0)
	v_mfma_f32_16x16x32_bf16 v[94:97], v[230:233], v[184:187], v[94:97]
	v_mfma_f32_16x16x32_bf16 v[90:93], v[238:241], v[184:187], v[90:93]
	v_mfma_f32_16x16x32_bf16 v[86:89], v[230:233], v[192:195], v[86:89]
	v_mfma_f32_16x16x32_bf16 v[70:73], v[238:241], v[192:195], v[70:73]
	v_mfma_f32_16x16x32_bf16 v[62:65], v[230:233], v[200:203], v[62:65]
	v_mfma_f32_16x16x32_bf16 v[58:61], v[238:241], v[200:203], v[58:61]
	v_mfma_f32_16x16x32_bf16 v[54:57], v[230:233], v[222:225], v[54:57]
	v_mfma_f32_16x16x32_bf16 v[50:53], v[238:241], v[222:225], v[50:53]
	v_mfma_f32_16x16x32_bf16 v[94:97], v[234:237], v[188:191], v[94:97]
	v_mfma_f32_16x16x32_bf16 v[90:93], v[242:245], v[188:191], v[90:93]
	v_mfma_f32_16x16x32_bf16 v[86:89], v[234:237], v[196:199], v[86:89]
	v_mfma_f32_16x16x32_bf16 v[70:73], v[242:245], v[196:199], v[70:73]
	v_mfma_f32_16x16x32_bf16 v[62:65], v[234:237], v[218:221], v[62:65]
	v_mfma_f32_16x16x32_bf16 v[58:61], v[242:245], v[218:221], v[58:61]
	v_mfma_f32_16x16x32_bf16 v[54:57], v[234:237], v[226:229], v[54:57]
	v_mfma_f32_16x16x32_bf16 v[50:53], v[242:245], v[226:229], v[50:53]
	s_setprio 0
	v_readfirstlane_b32 s59, v155
	v_lshl_add_u64 v[208:209], v[246:247], 0, s[84:85]
	s_mov_b32 m0, s59
	v_readfirstlane_b32 s59, v156
	s_barrier
	ds_read_b128 v[184:187], v0 offset:49152
	ds_read_b128 v[188:191], v0 offset:50176
	ds_read_b128 v[192:195], v0 offset:51200
	ds_read_b128 v[196:199], v0 offset:52224
	ds_read_b128 v[200:203], v0 offset:53248
	ds_read_b128 v[218:221], v0 offset:54272
	ds_read_b128 v[222:225], v0 offset:55296
	ds_read_b128 v[226:229], v0 offset:56320
	global_load_lds_dwordx4 v[208:209], off
	v_lshl_add_u64 v[208:209], v[248:249], 0, s[84:85]
	s_mov_b32 m0, s59
	s_nop 0
	global_load_lds_dwordx4 v[208:209], off
	s_waitcnt vmcnt(10)
	s_barrier
	s_waitcnt lgkmcnt(0)
	s_setprio 1
	s_waitcnt lgkmcnt(0)
	v_mfma_f32_16x16x32_bf16 v[46:49], v[162:165], v[184:187], v[46:49]
	v_mfma_f32_16x16x32_bf16 v[42:45], v[170:173], v[184:187], v[42:45]
	v_mfma_f32_16x16x32_bf16 v[38:41], v[162:165], v[192:195], v[38:41]
	v_mfma_f32_16x16x32_bf16 v[34:37], v[170:173], v[192:195], v[34:37]
	v_mfma_f32_16x16x32_bf16 v[30:33], v[162:165], v[200:203], v[30:33]
	v_mfma_f32_16x16x32_bf16 v[26:29], v[170:173], v[200:203], v[26:29]
	v_mfma_f32_16x16x32_bf16 v[22:25], v[162:165], v[222:225], v[22:25]
	v_mfma_f32_16x16x32_bf16 v[18:21], v[170:173], v[222:225], v[18:21]
	v_mfma_f32_16x16x32_bf16 v[46:49], v[166:169], v[188:191], v[46:49]
	v_mfma_f32_16x16x32_bf16 v[42:45], v[174:177], v[188:191], v[42:45]
	v_mfma_f32_16x16x32_bf16 v[38:41], v[166:169], v[196:199], v[38:41]
	v_mfma_f32_16x16x32_bf16 v[34:37], v[174:177], v[196:199], v[34:37]
	v_mfma_f32_16x16x32_bf16 v[30:33], v[166:169], v[218:221], v[30:33]
	v_mfma_f32_16x16x32_bf16 v[26:29], v[174:177], v[218:221], v[26:29]
	v_mfma_f32_16x16x32_bf16 v[22:25], v[166:169], v[226:229], v[22:25]
	v_mfma_f32_16x16x32_bf16 v[18:21], v[174:177], v[226:229], v[18:21]
	s_setprio 0
	s_barrier
	v_readfirstlane_b32 s59, v157
	v_lshl_add_u64 v[208:209], v[204:205], 0, s[86:87]
	s_mov_b32 m0, s59
	v_readfirstlane_b32 s59, v158
	global_load_lds_dwordx4 v[208:209], off
	v_lshl_add_u64 v[208:209], v[214:215], 0, s[86:87]
	s_mov_b32 m0, s59
	s_nop 0
	global_load_lds_dwordx4 v[208:209], off
	ds_read_b128 v[162:165], v145
	ds_read_b128 v[166:169], v145 offset:1024
	ds_read_b128 v[170:173], v145 offset:2048
	ds_read_b128 v[174:177], v145 offset:3072
	s_waitcnt vmcnt(6)
	s_barrier
; #define STAGE(P, BASE, LD, br, kt) do { const bf16* _gb = BASE + ((long)(br) * (LD) + (long)(kt) * BK); \
;     _Pragma("unroll") for (int _i = 0; _i < 2; ++_i) { \
;       __builtin_amdgcn_global_load_lds((const unsigned*)(_gb + ((&LD == &lda) ? offA[_i] : offB[_i])), \
;         (unsigned*)((char*)(P) + tidx_ * 16 + _i * 8192), 16, 0, 0); } } while (0)
; #define LDA(dst, b, h) _Pragma("unroll") for (int m = 0; m < 4; ++m) _Pragma("unroll") for (int k = 0; k < 2; ++k) \
;     dst[m][k] = *reinterpret_cast<const bf16x8*>(smem + (((b) * 2 + (h)) * 16384 + m * 2048 + k * 1024) + aoff)
; #define LDB(dst, b, h) _Pragma("unroll") for (int n = 0; n < 2; ++n) _Pragma("unroll") for (int k = 0; k < 2; ++k) \
;     dst[n][k] = *reinterpret_cast<const bf16x8*>(smem + (((b) * 2 + (h)) * 16384 + n * 2048 + k * 1024) + boff)
; #define MMA(ai, bj, At_, Bt_) do { __builtin_amdgcn_s_setprio(1); \
;     _Pragma("unroll") for (int m = 0; m < 4; ++m) _Pragma("unroll") for (int n = 0; n < 2; ++n) _Pragma("unroll") for (int k = 0; k < 2; ++k) \
;       acc[ai][bj][m][n] = __builtin_amdgcn_mfma_f32_16x16x32_bf16(Bt_[n][k], At_[m][k], acc[ai][bj][m][n], 0, 0, 0); \
;     __builtin_amdgcn_s_setprio(0); } while (0)
; #define WAIT_V(n) asm volatile("s_waitcnt vmcnt(" #n ")" ::: "memory")
; #define WAIT_L(n) asm volatile("s_waitcnt lgkmcnt(" #n ")" ::: "memory")
; #define BAR __builtin_amdgcn_s_barrier()
; template <class Epi, int NB>
; DEV void gemm_tile_nb(const bf16* __restrict__ A, int lda, long strideA, const bf16* __restrict__ Bt, int ldb, long strideB, int K, int brow, int bcol, Epi& epi) {
;     ...
;     WAIT_V(6); BAR; MMA(1, 1, At, B1); BAR;
;   }
;   { LDB(B0, 0, 0); LDA(At, 0, 0); STAGE(SA(1, 1), A, lda, brow + HALF, nt - 1);
;     BAR; WAIT_L(0); MMA(0, 0, At, B0); BAR;
;     LDB(B1, 0, 1); BAR; WAIT_L(0); MMA(0, 1, At, B1); BAR;
;     LDA(At, 0, 1); WAIT_V(4); BAR; WAIT_L(0); MMA(1, 0, At, B0); MMA(1, 1, At, B1); BAR; }
;   { LDB(B0, 1, 0); LDA(At, 1, 0); WAIT_V(2); BAR; WAIT_L(0); MMA(0, 0, At, B0); BAR;
	s_setprio 1
	v_mfma_f32_16x16x32_bf16 v[14:17], v[230:233], v[184:187], v[14:17]
	v_mfma_f32_16x16x32_bf16 v[10:13], v[238:241], v[184:187], v[10:13]
	v_mfma_f32_16x16x32_bf16 v[6:9], v[230:233], v[192:195], v[6:9]
	v_mfma_f32_16x16x32_bf16 v[2:5], v[238:241], v[192:195], v[2:5]
	v_mfma_f32_16x16x32_bf16 v[66:69], v[230:233], v[200:203], v[66:69]
	v_mfma_f32_16x16x32_bf16 v[74:77], v[238:241], v[200:203], v[74:77]
	v_mfma_f32_16x16x32_bf16 v[78:81], v[230:233], v[222:225], v[78:81]
	v_mfma_f32_16x16x32_bf16 v[82:85], v[238:241], v[222:225], v[82:85]
	v_mfma_f32_16x16x32_bf16 v[14:17], v[234:237], v[188:191], v[14:17]
	v_mfma_f32_16x16x32_bf16 v[10:13], v[242:245], v[188:191], v[10:13]
	v_mfma_f32_16x16x32_bf16 v[6:9], v[234:237], v[196:199], v[6:9]
	v_mfma_f32_16x16x32_bf16 v[2:5], v[242:245], v[196:199], v[2:5]
	v_mfma_f32_16x16x32_bf16 v[66:69], v[234:237], v[218:221], v[66:69]
	v_mfma_f32_16x16x32_bf16 v[74:77], v[242:245], v[218:221], v[74:77]
	v_mfma_f32_16x16x32_bf16 v[78:81], v[234:237], v[226:229], v[78:81]
	v_mfma_f32_16x16x32_bf16 v[82:85], v[242:245], v[226:229], v[82:85]
	s_setprio 0
	s_add_i32 s58, s58, 2
	s_add_u32 s42, s42, 0x100
	s_addc_u32 s43, s43, 0
	s_cmp_lt_u32 s58, 12
	s_barrier
	s_cbranch_scc1 .LBB0_960
	s_mov_b64 s[58:59], 0x780
	v_readfirstlane_b32 s42, v159
	v_lshl_add_u64 v[132:133], v[132:133], 0, s[58:59]
	s_mov_b32 m0, s42
	v_readfirstlane_b32 s42, v160
	ds_read_b128 v[134:137], v145
	ds_read_b128 v[138:141], v145 offset:1024
	ds_read_b128 v[146:149], v145 offset:2048
	ds_read_b128 v[150:153], v145 offset:3072
	ds_read_b128 v[154:157], v0
	ds_read_b128 v[162:165], v0 offset:1024
	ds_read_b128 v[166:169], v0 offset:2048
	ds_read_b128 v[170:173], v0 offset:3072
	ds_read_b128 v[174:177], v0 offset:4096
	ds_read_b128 v[184:187], v0 offset:5120
	ds_read_b128 v[188:191], v0 offset:6144
	ds_read_b128 v[192:195], v0 offset:7168
	global_load_lds_dwordx4 v[132:133], off
	v_lshl_add_u64 v[130:131], v[130:131], 0, s[58:59]
	s_mov_b32 m0, s42
	s_cmpk_gt_u32 s57, 0xff
	global_load_lds_dwordx4 v[130:131], off
	s_barrier
	s_waitcnt lgkmcnt(0)
	s_setprio 1
	s_waitcnt lgkmcnt(0)
	v_mfma_f32_16x16x32_bf16 v[126:129], v[134:137], v[154:157], v[126:129]
	v_mfma_f32_16x16x32_bf16 v[118:121], v[134:137], v[166:169], v[118:121]
	v_mfma_f32_16x16x32_bf16 v[110:113], v[134:137], v[174:177], v[110:113]
	v_mfma_f32_16x16x32_bf16 v[102:105], v[134:137], v[188:191], v[102:105]
	v_mfma_f32_16x16x32_bf16 v[126:129], v[138:141], v[162:165], v[126:129]
	v_mfma_f32_16x16x32_bf16 v[122:125], v[146:149], v[154:157], v[122:125]
	v_mfma_f32_16x16x32_bf16 v[118:121], v[138:141], v[170:173], v[118:121]
	v_mfma_f32_16x16x32_bf16 v[114:117], v[146:149], v[166:169], v[114:117]
	v_mfma_f32_16x16x32_bf16 v[110:113], v[138:141], v[184:187], v[110:113]
	v_mfma_f32_16x16x32_bf16 v[106:109], v[146:149], v[174:177], v[106:109]
	v_mfma_f32_16x16x32_bf16 v[102:105], v[138:141], v[192:195], v[102:105]
	v_mfma_f32_16x16x32_bf16 v[98:101], v[146:149], v[188:191], v[98:101]
	v_mfma_f32_16x16x32_bf16 v[130:133], v[150:153], v[162:165], v[122:125]
	v_mfma_f32_16x16x32_bf16 v[158:161], v[150:153], v[170:173], v[114:117]
	v_mfma_f32_16x16x32_bf16 v[196:199], v[150:153], v[184:187], v[106:109]
	v_mfma_f32_16x16x32_bf16 v[200:203], v[150:153], v[192:195], v[98:101]
	s_setprio 0
	s_barrier
	s_nop 1
	ds_read_b128 v[98:101], v145 offset:16384
	ds_read_b128 v[106:109], v145 offset:17408
	ds_read_b128 v[114:117], v145 offset:18432
	ds_read_b128 v[122:125], v145 offset:19456
	s_barrier
	s_waitcnt lgkmcnt(0)
	s_setprio 1
	s_waitcnt lgkmcnt(0)
	v_mfma_f32_16x16x32_bf16 v[94:97], v[98:101], v[154:157], v[94:97]
	v_mfma_f32_16x16x32_bf16 v[86:89], v[98:101], v[166:169], v[86:89]
	v_mfma_f32_16x16x32_bf16 v[70:73], v[114:117], v[166:169], v[70:73]
	v_mfma_f32_16x16x32_bf16 v[62:65], v[98:101], v[174:177], v[62:65]
	v_mfma_f32_16x16x32_bf16 v[58:61], v[114:117], v[174:177], v[58:61]
	v_mfma_f32_16x16x32_bf16 v[54:57], v[98:101], v[188:191], v[54:57]
	v_mfma_f32_16x16x32_bf16 v[50:53], v[114:117], v[188:191], v[50:53]
	v_mfma_f32_16x16x32_bf16 v[94:97], v[106:109], v[162:165], v[94:97]
	v_mfma_f32_16x16x32_bf16 v[90:93], v[114:117], v[154:157], v[90:93]
	v_mfma_f32_16x16x32_bf16 v[86:89], v[106:109], v[170:173], v[86:89]
	v_mfma_f32_16x16x32_bf16 v[70:73], v[122:125], v[170:173], v[70:73]
	v_mfma_f32_16x16x32_bf16 v[62:65], v[106:109], v[184:187], v[62:65]
	v_mfma_f32_16x16x32_bf16 v[58:61], v[122:125], v[184:187], v[58:61]
	v_mfma_f32_16x16x32_bf16 v[54:57], v[106:109], v[192:195], v[54:57]
	v_mfma_f32_16x16x32_bf16 v[50:53], v[122:125], v[192:195], v[50:53]
	v_mfma_f32_16x16x32_bf16 v[154:157], v[122:125], v[162:165], v[90:93]
	s_setprio 0
	s_barrier
	s_nop 0
	ds_read_b128 v[90:93], v0 offset:16384
	ds_read_b128 v[162:165], v0 offset:17408
	ds_read_b128 v[166:169], v0 offset:18432
	ds_read_b128 v[170:173], v0 offset:19456
	ds_read_b128 v[174:177], v0 offset:20480
	ds_read_b128 v[184:187], v0 offset:21504
	ds_read_b128 v[188:191], v0 offset:22528
	ds_read_b128 v[192:195], v0 offset:23552
	s_waitcnt vmcnt(4)
	s_barrier
; #define LDA(dst, b, h) _Pragma("unroll") for (int m = 0; m < 4; ++m) _Pragma("unroll") for (int k = 0; k < 2; ++k) \
;     dst[m][k] = *reinterpret_cast<const bf16x8*>(smem + (((b) * 2 + (h)) * 16384 + m * 2048 + k * 1024) + aoff)
; #define LDB(dst, b, h) _Pragma("unroll") for (int n = 0; n < 2; ++n) _Pragma("unroll") for (int k = 0; k < 2; ++k) \
;     dst[n][k] = *reinterpret_cast<const bf16x8*>(smem + (((b) * 2 + (h)) * 16384 + n * 2048 + k * 1024) + boff)
; #define MMA(ai, bj, At_, Bt_) do { __builtin_amdgcn_s_setprio(1); \
;     _Pragma("unroll") for (int m = 0; m < 4; ++m) _Pragma("unroll") for (int n = 0; n < 2; ++n) _Pragma("unroll") for (int k = 0; k < 2; ++k) \
;       acc[ai][bj][m][n] = __builtin_amdgcn_mfma_f32_16x16x32_bf16(Bt_[n][k], At_[m][k], acc[ai][bj][m][n], 0, 0, 0); \
;     __builtin_amdgcn_s_setprio(0); } while (0)
; #define WAIT_V(n) asm volatile("s_waitcnt vmcnt(" #n ")" ::: "memory")
; #define WAIT_L(n) asm volatile("s_waitcnt lgkmcnt(" #n ")" ::: "memory")
; #define BAR __builtin_amdgcn_s_barrier()
; template <class Epi, int NB>
; DEV void gemm_tile_nb(const bf16* __restrict__ A, int lda, long strideA, const bf16* __restrict__ Bt, int ldb, long strideB, int K, int brow, int bcol, Epi& epi) {
;     ...
;     LDA(At, 0, 1); WAIT_V(4); BAR; WAIT_L(0); MMA(1, 0, At, B0); MMA(1, 1, At, B1); BAR; }
;   { LDB(B0, 1, 0); LDA(At, 1, 0); WAIT_V(2); BAR; WAIT_L(0); MMA(0, 0, At, B0); BAR;
;     LDB(B1, 1, 1); WAIT_V(0); BAR; WAIT_L(0); MMA(0, 1, At, B1); BAR;
;     LDA(At, 1, 1); BAR; WAIT_L(0); MMA(1, 0, At, B0); MMA(1, 1, At, B1); BAR; }
	s_waitcnt lgkmcnt(0)
	s_setprio 1
	s_waitcnt lgkmcnt(0)
	v_mfma_f32_16x16x32_bf16 v[46:49], v[134:137], v[90:93], v[46:49]
	v_mfma_f32_16x16x32_bf16 v[42:45], v[146:149], v[90:93], v[42:45]
	v_mfma_f32_16x16x32_bf16 v[38:41], v[134:137], v[166:169], v[38:41]
	v_mfma_f32_16x16x32_bf16 v[34:37], v[146:149], v[166:169], v[34:37]
	v_mfma_f32_16x16x32_bf16 v[30:33], v[134:137], v[174:177], v[30:33]
	v_mfma_f32_16x16x32_bf16 v[22:25], v[134:137], v[188:191], v[22:25]
	v_mfma_f32_16x16x32_bf16 v[46:49], v[138:141], v[162:165], v[46:49]
	v_mfma_f32_16x16x32_bf16 v[42:45], v[150:153], v[162:165], v[42:45]
	v_mfma_f32_16x16x32_bf16 v[38:41], v[138:141], v[170:173], v[38:41]
	v_mfma_f32_16x16x32_bf16 v[34:37], v[150:153], v[170:173], v[34:37]
	v_mfma_f32_16x16x32_bf16 v[30:33], v[138:141], v[184:187], v[30:33]
	v_mfma_f32_16x16x32_bf16 v[26:29], v[146:149], v[174:177], v[26:29]
	v_mfma_f32_16x16x32_bf16 v[22:25], v[138:141], v[192:195], v[22:25]
	v_mfma_f32_16x16x32_bf16 v[18:21], v[146:149], v[188:191], v[18:21]
	v_mfma_f32_16x16x32_bf16 v[218:221], v[150:153], v[184:187], v[26:29]
	v_mfma_f32_16x16x32_bf16 v[134:137], v[150:153], v[192:195], v[18:21]
	s_setprio 0
	s_setprio 1
	v_mfma_f32_16x16x32_bf16 v[2:5], v[114:117], v[166:169], v[2:5]
	v_mfma_f32_16x16x32_bf16 v[146:149], v[122:125], v[170:173], v[2:5]
	v_mfma_f32_16x16x32_bf16 v[2:5], v[98:101], v[174:177], v[66:69]
	v_mfma_f32_16x16x32_bf16 v[14:17], v[98:101], v[90:93], v[14:17]
	v_mfma_f32_16x16x32_bf16 v[10:13], v[114:117], v[90:93], v[10:13]
	v_mfma_f32_16x16x32_bf16 v[150:153], v[106:109], v[184:187], v[2:5]
	v_mfma_f32_16x16x32_bf16 v[2:5], v[114:117], v[174:177], v[74:77]
	v_mfma_f32_16x16x32_bf16 v[14:17], v[106:109], v[162:165], v[14:17]
	v_mfma_f32_16x16x32_bf16 v[138:141], v[122:125], v[162:165], v[10:13]
	v_mfma_f32_16x16x32_bf16 v[6:9], v[98:101], v[166:169], v[6:9]
	v_mfma_f32_16x16x32_bf16 v[162:165], v[122:125], v[184:187], v[2:5]
	v_mfma_f32_16x16x32_bf16 v[2:5], v[98:101], v[188:191], v[78:81]
	v_mfma_f32_16x16x32_bf16 v[6:9], v[106:109], v[170:173], v[6:9]
	v_mfma_f32_16x16x32_bf16 v[166:169], v[106:109], v[192:195], v[2:5]
	v_mfma_f32_16x16x32_bf16 v[2:5], v[114:117], v[188:191], v[82:85]
	v_mfma_f32_16x16x32_bf16 v[170:173], v[122:125], v[192:195], v[2:5]
	s_setprio 0
	s_barrier
	s_nop 4
	ds_read_b128 v[2:5], v145 offset:32768
	ds_read_b128 v[10:13], v145 offset:33792
	ds_read_b128 v[174:177], v145 offset:34816
	ds_read_b128 v[184:187], v145 offset:35840
	ds_read_b128 v[18:21], v0 offset:32768
	ds_read_b128 v[26:29], v0 offset:33792
	ds_read_b128 v[78:81], v0 offset:34816
	ds_read_b128 v[188:191], v0 offset:35840
	ds_read_b128 v[192:195], v0 offset:36864
	ds_read_b128 v[222:225], v0 offset:37888
	ds_read_b128 v[226:229], v0 offset:38912
	ds_read_b128 v[230:233], v0 offset:39936
	s_waitcnt vmcnt(2)
	s_barrier
	s_waitcnt lgkmcnt(0)
	s_setprio 1
	s_waitcnt lgkmcnt(0)
	v_mfma_f32_16x16x32_bf16 v[66:69], v[2:5], v[18:21], v[126:129]
	v_mfma_f32_16x16x32_bf16 v[122:125], v[10:13], v[26:29], v[66:69]
	v_mfma_f32_16x16x32_bf16 v[66:69], v[174:177], v[18:21], v[130:133]
	v_mfma_f32_16x16x32_bf16 v[114:117], v[184:187], v[26:29], v[66:69]
	v_mfma_f32_16x16x32_bf16 v[66:69], v[2:5], v[78:81], v[118:121]
	v_mfma_f32_16x16x32_bf16 v[106:109], v[10:13], v[188:191], v[66:69]
	v_mfma_f32_16x16x32_bf16 v[66:69], v[174:177], v[78:81], v[158:161]
	v_mfma_f32_16x16x32_bf16 v[98:101], v[184:187], v[188:191], v[66:69]
	v_mfma_f32_16x16x32_bf16 v[66:69], v[2:5], v[192:195], v[110:113]
	v_mfma_f32_16x16x32_bf16 v[90:93], v[10:13], v[222:225], v[66:69]
	v_mfma_f32_16x16x32_bf16 v[66:69], v[174:177], v[192:195], v[196:199]
	v_mfma_f32_16x16x32_bf16 v[82:85], v[184:187], v[222:225], v[66:69]
	v_mfma_f32_16x16x32_bf16 v[66:69], v[2:5], v[226:229], v[102:105]
	v_mfma_f32_16x16x32_bf16 v[74:77], v[10:13], v[230:233], v[66:69]
	v_mfma_f32_16x16x32_bf16 v[66:69], v[174:177], v[226:229], v[200:203]
	v_mfma_f32_16x16x32_bf16 v[66:69], v[184:187], v[230:233], v[66:69]
	s_setprio 0
	s_barrier
; #define LDA(dst, b, h) _Pragma("unroll") for (int m = 0; m < 4; ++m) _Pragma("unroll") for (int k = 0; k < 2; ++k) \
;     dst[m][k] = *reinterpret_cast<const bf16x8*>(smem + (((b) * 2 + (h)) * 16384 + m * 2048 + k * 1024) + aoff)
; #define LDB(dst, b, h) _Pragma("unroll") for (int n = 0; n < 2; ++n) _Pragma("unroll") for (int k = 0; k < 2; ++k) \
;     dst[n][k] = *reinterpret_cast<const bf16x8*>(smem + (((b) * 2 + (h)) * 16384 + n * 2048 + k * 1024) + boff)
; #define MMA(ai, bj, At_, Bt_) do { __builtin_amdgcn_s_setprio(1); \
;     _Pragma("unroll") for (int m = 0; m < 4; ++m) _Pragma("unroll") for (int n = 0; n < 2; ++n) _Pragma("unroll") for (int k = 0; k < 2; ++k) \
;       acc[ai][bj][m][n] = __builtin_amdgcn_mfma_f32_16x16x32_bf16(Bt_[n][k], At_[m][k], acc[ai][bj][m][n], 0, 0, 0); \
;     __builtin_amdgcn_s_setprio(0); } while (0)
; #define WAIT_V(n) asm volatile("s_waitcnt vmcnt(" #n ")" ::: "memory")
; #define WAIT_L(n) asm volatile("s_waitcnt lgkmcnt(" #n ")" ::: "memory")
; #define BAR __builtin_amdgcn_s_barrier()
; template <class Epi, int NB>
; DEV void gemm_tile_nb(const bf16* __restrict__ A, int lda, long strideA, const bf16* __restrict__ Bt, int ldb, long strideB, int K, int brow, int bcol, Epi& epi) {
;     ...
;   { LDB(B0, 1, 0); LDA(At, 1, 0); WAIT_V(2); BAR; WAIT_L(0); MMA(0, 0, At, B0); BAR;
;     LDB(B1, 1, 1); WAIT_V(0); BAR; WAIT_L(0); MMA(0, 1, At, B1); BAR;
;     LDA(At, 1, 1); BAR; WAIT_L(0); MMA(1, 0, At, B0); MMA(1, 1, At, B1); BAR; }
;   if (wr == 0) BAR;
	ds_read_b128 v[130:133], v145 offset:49152
	ds_read_b128 v[158:161], v145 offset:50176
	ds_read_b128 v[196:199], v145 offset:51200
	ds_read_b128 v[200:203], v145 offset:52224
	s_waitcnt vmcnt(0)
	s_barrier
	s_waitcnt lgkmcnt(0)
	s_setprio 1
	s_waitcnt lgkmcnt(0)
	v_mfma_f32_16x16x32_bf16 v[94:97], v[130:133], v[18:21], v[94:97]
	v_mfma_f32_16x16x32_bf16 v[18:21], v[196:199], v[18:21], v[154:157]
	v_mfma_f32_16x16x32_bf16 v[118:121], v[200:203], v[26:29], v[18:21]
	v_mfma_f32_16x16x32_bf16 v[18:21], v[130:133], v[78:81], v[86:89]
	v_mfma_f32_16x16x32_bf16 v[110:113], v[158:161], v[188:191], v[18:21]
	v_mfma_f32_16x16x32_bf16 v[18:21], v[196:199], v[78:81], v[70:73]
	v_mfma_f32_16x16x32_bf16 v[102:105], v[200:203], v[188:191], v[18:21]
	v_mfma_f32_16x16x32_bf16 v[18:21], v[130:133], v[192:195], v[62:65]
	v_mfma_f32_16x16x32_bf16 v[126:129], v[158:161], v[26:29], v[94:97]
	v_mfma_f32_16x16x32_bf16 v[94:97], v[158:161], v[222:225], v[18:21]
	v_mfma_f32_16x16x32_bf16 v[18:21], v[196:199], v[192:195], v[58:61]
	v_mfma_f32_16x16x32_bf16 v[86:89], v[200:203], v[222:225], v[18:21]
	v_mfma_f32_16x16x32_bf16 v[18:21], v[130:133], v[226:229], v[54:57]
	v_mfma_f32_16x16x32_bf16 v[78:81], v[158:161], v[230:233], v[18:21]
	v_mfma_f32_16x16x32_bf16 v[18:21], v[196:199], v[226:229], v[50:53]
	v_mfma_f32_16x16x32_bf16 v[70:73], v[200:203], v[230:233], v[18:21]
	s_setprio 0
	s_barrier
	ds_read_b128 v[54:57], v0 offset:49152
	ds_read_b128 v[154:157], v0 offset:50176
	ds_read_b128 v[188:191], v0 offset:51200
	ds_read_b128 v[192:195], v0 offset:52224
	ds_read_b128 v[222:225], v0 offset:53248
	ds_read_b128 v[226:229], v0 offset:54272
	ds_read_b128 v[230:233], v0 offset:55296
	ds_read_b128 v[234:237], v0 offset:56320
	s_barrier
	s_waitcnt lgkmcnt(0)
	s_setprio 1
	s_waitcnt lgkmcnt(0)
	v_mfma_f32_16x16x32_bf16 v[18:21], v[2:5], v[54:57], v[46:49]
	v_mfma_f32_16x16x32_bf16 v[58:61], v[10:13], v[154:157], v[18:21]
	v_mfma_f32_16x16x32_bf16 v[18:21], v[174:177], v[54:57], v[42:45]
	v_mfma_f32_16x16x32_bf16 v[50:53], v[184:187], v[154:157], v[18:21]
	v_mfma_f32_16x16x32_bf16 v[18:21], v[2:5], v[188:191], v[38:41]
	v_mfma_f32_16x16x32_bf16 v[42:45], v[10:13], v[192:195], v[18:21]
	v_mfma_f32_16x16x32_bf16 v[18:21], v[174:177], v[188:191], v[34:37]
	v_mfma_f32_16x16x32_bf16 v[34:37], v[184:187], v[192:195], v[18:21]
	v_mfma_f32_16x16x32_bf16 v[18:21], v[2:5], v[222:225], v[30:33]
	v_mfma_f32_16x16x32_bf16 v[2:5], v[2:5], v[230:233], v[22:25]
	v_mfma_f32_16x16x32_bf16 v[26:29], v[10:13], v[226:229], v[18:21]
	v_mfma_f32_16x16x32_bf16 v[18:21], v[174:177], v[222:225], v[218:221]
	v_mfma_f32_16x16x32_bf16 v[10:13], v[10:13], v[234:237], v[2:5]
	v_mfma_f32_16x16x32_bf16 v[2:5], v[174:177], v[230:233], v[134:137]
	v_mfma_f32_16x16x32_bf16 v[18:21], v[184:187], v[226:229], v[18:21]
	v_mfma_f32_16x16x32_bf16 v[2:5], v[184:187], v[234:237], v[2:5]
	s_setprio 0
	s_setprio 1
	v_mfma_f32_16x16x32_bf16 v[6:9], v[130:133], v[188:191], v[6:9]
	v_mfma_f32_16x16x32_bf16 v[46:49], v[158:161], v[192:195], v[6:9]
	v_mfma_f32_16x16x32_bf16 v[6:9], v[196:199], v[188:191], v[146:149]
	v_mfma_f32_16x16x32_bf16 v[38:41], v[200:203], v[192:195], v[6:9]
	v_mfma_f32_16x16x32_bf16 v[6:9], v[130:133], v[222:225], v[150:153]
	v_mfma_f32_16x16x32_bf16 v[14:17], v[130:133], v[54:57], v[14:17]
	v_mfma_f32_16x16x32_bf16 v[30:33], v[158:161], v[226:229], v[6:9]
	v_mfma_f32_16x16x32_bf16 v[6:9], v[196:199], v[222:225], v[162:165]
	v_mfma_f32_16x16x32_bf16 v[62:65], v[158:161], v[154:157], v[14:17]
	v_mfma_f32_16x16x32_bf16 v[14:17], v[196:199], v[54:57], v[138:141]
	v_mfma_f32_16x16x32_bf16 v[22:25], v[200:203], v[226:229], v[6:9]
	v_mfma_f32_16x16x32_bf16 v[6:9], v[130:133], v[230:233], v[166:169]
	v_mfma_f32_16x16x32_bf16 v[54:57], v[200:203], v[154:157], v[14:17]
	v_mfma_f32_16x16x32_bf16 v[14:17], v[158:161], v[234:237], v[6:9]
	v_mfma_f32_16x16x32_bf16 v[6:9], v[196:199], v[230:233], v[170:173]
	v_mfma_f32_16x16x32_bf16 v[6:9], v[200:203], v[234:237], v[6:9]
	s_setprio 0
	s_barrier
	s_cbranch_scc1 .LBB0_956
	s_barrier
	s_branch .LBB0_956
